# selection threshold search starts from the largest candidate's binade when at least 16 candidates reach it (skips 9 dependent ballot steps), else the full search
# speedup vs baseline: 1.1940x; 1.0006x over previous
.LBB0_867:
	s_waitcnt lgkmcnt(14)
	ds_read_b32 v4, v3
	ds_read_b32 v5, v2
	s_waitcnt lgkmcnt(1)
	v_and_b32_e32 v6, 0xffffff80, v4
	s_waitcnt lgkmcnt(0)
	v_and_b32_e32 v7, 0xffffff80, v5
	v_add_f32_e32 v6, v6, v7
	v_cndmask_b32_e64 v6, v212, v6, s[4:5]
	v_ashrrev_i32_e32 v7, 31, v6
	v_or_b32_e32 v7, 0x80000000, v7
	v_xor_b32_e32 v7, v7, v6
	s_nop 0
	v_readlane_b32 s1, v7, 0
	s_and_b32 s1, s1, 0xff800000
	v_cmp_le_u32_e64 s[42:43], s1, v7
	s_bcnt1_i32_b64 s41, s[42:43]
	s_mov_b32 s0, s1
	s_cmp_gt_u32 s41, 15
	s_cbranch_scc1 .Lpeer_thresh_b22
	s_mov_b32 s0, 0
	s_or_b32 s1, s0, 0x80000000
	v_cmp_le_u32_e64 s[42:43], s1, v7
	s_bcnt1_i32_b64 s41, s[42:43]
	s_cmp_gt_u32 s41, 15
	s_cselect_b32 s0, s1, s0
	s_or_b32 s1, s0, 0x40000000
	v_cmp_le_u32_e64 s[42:43], s1, v7
	s_bcnt1_i32_b64 s41, s[42:43]
	s_cmp_gt_u32 s41, 15
	s_cselect_b32 s0, s1, s0
	s_or_b32 s1, s0, 0x20000000
	v_cmp_le_u32_e64 s[42:43], s1, v7
	s_bcnt1_i32_b64 s41, s[42:43]
	s_cmp_gt_u32 s41, 15
	s_cselect_b32 s0, s1, s0
	s_or_b32 s1, s0, 0x10000000
	v_cmp_le_u32_e64 s[42:43], s1, v7
	s_bcnt1_i32_b64 s41, s[42:43]
	s_cmp_gt_u32 s41, 15
	s_cselect_b32 s0, s1, s0
	s_or_b32 s1, s0, 0x8000000
	v_cmp_le_u32_e64 s[42:43], s1, v7
	s_bcnt1_i32_b64 s41, s[42:43]
	s_cmp_gt_u32 s41, 15
	s_cselect_b32 s0, s1, s0
	s_or_b32 s1, s0, 0x4000000
	v_cmp_le_u32_e64 s[42:43], s1, v7
	s_bcnt1_i32_b64 s41, s[42:43]
	s_cmp_gt_u32 s41, 15
	s_cselect_b32 s0, s1, s0
	s_or_b32 s1, s0, 0x2000000
	v_cmp_le_u32_e64 s[42:43], s1, v7
	s_bcnt1_i32_b64 s41, s[42:43]
	s_cmp_gt_u32 s41, 15
	s_cselect_b32 s0, s1, s0
	s_or_b32 s1, s0, 0x1000000
	v_cmp_le_u32_e64 s[42:43], s1, v7
	s_bcnt1_i32_b64 s41, s[42:43]
	s_cmp_gt_u32 s41, 15
	s_cselect_b32 s0, s1, s0
	s_or_b32 s1, s0, 0x800000
	v_cmp_le_u32_e64 s[42:43], s1, v7
	s_bcnt1_i32_b64 s41, s[42:43]
	s_cmp_gt_u32 s41, 15
	s_cselect_b32 s0, s1, s0
.Lpeer_thresh_b22:
	s_or_b32 s1, s0, 0x400000
	v_cmp_le_u32_e64 s[42:43], s1, v7
	s_bcnt1_i32_b64 s41, s[42:43]
	s_cmp_gt_u32 s41, 15
	s_cselect_b32 s0, s1, s0
	s_or_b32 s1, s0, 0x200000
	v_cmp_le_u32_e64 s[42:43], s1, v7
	s_bcnt1_i32_b64 s41, s[42:43]
	s_cmp_gt_u32 s41, 15
	s_cselect_b32 s0, s1, s0
	s_or_b32 s1, s0, 0x100000
	v_cmp_le_u32_e64 s[42:43], s1, v7
	s_bcnt1_i32_b64 s41, s[42:43]
	s_cmp_gt_u32 s41, 15
	s_cselect_b32 s0, s1, s0
	s_or_b32 s1, s0, 0x80000
	v_cmp_le_u32_e64 s[42:43], s1, v7
	s_bcnt1_i32_b64 s41, s[42:43]
	s_cmp_gt_u32 s41, 15
	s_cselect_b32 s0, s1, s0
	s_or_b32 s1, s0, 0x40000
	v_cmp_le_u32_e64 s[42:43], s1, v7
	s_bcnt1_i32_b64 s41, s[42:43]
	s_cmp_gt_u32 s41, 15
	s_cselect_b32 s0, s1, s0
	s_or_b32 s1, s0, 0x20000
	v_cmp_le_u32_e64 s[42:43], s1, v7
	s_bcnt1_i32_b64 s41, s[42:43]
	s_cmp_gt_u32 s41, 15
	s_cselect_b32 s0, s1, s0
	s_or_b32 s1, s0, 0x10000
	v_cmp_le_u32_e64 s[42:43], s1, v7
	s_bcnt1_i32_b64 s41, s[42:43]
	s_cmp_gt_u32 s41, 15
	s_cselect_b32 s0, s1, s0
	s_or_b32 s1, s0, 0x8000
	v_cmp_le_u32_e64 s[42:43], s1, v7
	s_bcnt1_i32_b64 s41, s[42:43]
	s_cmp_gt_u32 s41, 15
	s_cselect_b32 s0, s1, s0
	s_or_b32 s1, s0, 0x4000
	v_cmp_le_u32_e64 s[42:43], s1, v7
	s_bcnt1_i32_b64 s41, s[42:43]
	s_cmp_gt_u32 s41, 15
	s_cselect_b32 s0, s1, s0
	s_or_b32 s1, s0, 0x2000
	v_cmp_le_u32_e64 s[42:43], s1, v7
	s_bcnt1_i32_b64 s41, s[42:43]
	s_cmp_gt_u32 s41, 15
	s_cselect_b32 s0, s1, s0
	s_or_b32 s1, s0, 0x1000
	v_cmp_le_u32_e64 s[42:43], s1, v7
	s_bcnt1_i32_b64 s41, s[42:43]
	s_cmp_gt_u32 s41, 15
	s_cselect_b32 s0, s1, s0
	v_cmp_le_u32_e64 s[42:43], s0, v7
	s_bcnt1_i32_b64 s41, s[42:43]
	s_cmp_eq_u32 s41, 16
	s_cbranch_scc1 .Lpeer_thresh_done
	s_or_b32 s1, s0, 0x800
	v_cmp_le_u32_e64 s[42:43], s1, v7
	s_bcnt1_i32_b64 s41, s[42:43]
	s_cmp_gt_u32 s41, 15
	s_cselect_b32 s0, s1, s0
	s_or_b32 s1, s0, 0x400
	v_cmp_le_u32_e64 s[42:43], s1, v7
	s_bcnt1_i32_b64 s41, s[42:43]
	s_cmp_gt_u32 s41, 15
	s_cselect_b32 s0, s1, s0
	s_or_b32 s1, s0, 0x200
	v_cmp_le_u32_e64 s[42:43], s1, v7
	s_bcnt1_i32_b64 s41, s[42:43]
	s_cmp_gt_u32 s41, 15
	s_cselect_b32 s0, s1, s0
	s_or_b32 s1, s0, 0x100
	v_cmp_le_u32_e64 s[42:43], s1, v7
	s_bcnt1_i32_b64 s41, s[42:43]
	s_cmp_gt_u32 s41, 15
	s_cselect_b32 s0, s1, s0
	s_or_b32 s1, s0, 0x80
	v_cmp_le_u32_e64 s[42:43], s1, v7
	s_bcnt1_i32_b64 s41, s[42:43]
	s_cmp_gt_u32 s41, 15
	s_cselect_b32 s0, s1, s0
	s_or_b32 s1, s0, 0x40
	v_cmp_le_u32_e64 s[42:43], s1, v7
	s_bcnt1_i32_b64 s41, s[42:43]
	s_cmp_gt_u32 s41, 15
	s_cselect_b32 s0, s1, s0
	s_or_b32 s1, s0, 0x20
	v_cmp_le_u32_e64 s[42:43], s1, v7
	s_bcnt1_i32_b64 s41, s[42:43]
	s_cmp_gt_u32 s41, 15
	s_cselect_b32 s0, s1, s0
	s_or_b32 s1, s0, 0x10
	v_cmp_le_u32_e64 s[42:43], s1, v7
	s_bcnt1_i32_b64 s41, s[42:43]
	s_cmp_gt_u32 s41, 15
	s_cselect_b32 s0, s1, s0
	s_or_b32 s1, s0, 0x8
	v_cmp_le_u32_e64 s[42:43], s1, v7
	s_bcnt1_i32_b64 s41, s[42:43]
	s_cmp_gt_u32 s41, 15
	s_cselect_b32 s0, s1, s0
	s_or_b32 s1, s0, 0x4
	v_cmp_le_u32_e64 s[42:43], s1, v7
	s_bcnt1_i32_b64 s41, s[42:43]
	s_cmp_gt_u32 s41, 15
	s_cselect_b32 s0, s1, s0
	s_or_b32 s1, s0, 0x2
	v_cmp_le_u32_e64 s[42:43], s1, v7
	s_bcnt1_i32_b64 s41, s[42:43]
	s_cmp_gt_u32 s41, 15
	s_cselect_b32 s0, s1, s0
	s_or_b32 s1, s0, 0x1
	v_cmp_le_u32_e64 s[42:43], s1, v7
	s_bcnt1_i32_b64 s41, s[42:43]
	s_cmp_gt_u32 s41, 15
	s_cselect_b32 s0, s1, s0
